# quarter K loops 2 and 4 placed at an 8-byte phase (dead padding only)
# baseline (speedup 1.0000x reference)
; #define PG8_STAGE(bufoff, gbase, voff) do { _Pragma("unroll") for (int _i = 0; _i < 2; ++_i) \
;         __builtin_amdgcn_global_load_lds((const unsigned*)((const char*)(gbase) + (voff)[_i]), (PG8_LAS unsigned*)(lds + (bufoff) + ldsw + _i * 8192), 16, 0, 0); } while (0)
; #define PG8_LDA(dst, b, h) do { _Pragma("unroll") for (int m = 0; m < 4; ++m) _Pragma("unroll") for (int k = 0; k < 2; ++k) dst[m][k] = *(const PG8_LAS bf16x8*)(lds + PG8_SA(b, h) + aoff + m * 2048 + k * 1024); } while (0)
; #define PG8_LDB(dst, b, h) do { _Pragma("unroll") for (int n = 0; n < 2; ++n) _Pragma("unroll") for (int k = 0; k < 2; ++k) dst[n][k] = *(const PG8_LAS bf16x8*)(lds + PG8_SB(b, h) + boff + n * 2048 + k * 1024); } while (0)
; #define PG8_MMA(ai, bj, At, Bt) do { __builtin_amdgcn_s_setprio(1); _Pragma("unroll") for (int m = 0; m < 4; ++m) _Pragma("unroll") for (int n = 0; n < 2; ++n) _Pragma("unroll") for (int k = 0; k < 2; ++k) \
;         acc[ai][bj][m][n] = __builtin_amdgcn_mfma_f32_16x16x32_bf16(Bt[n][k], At[m][k], acc[ai][bj][m][n], 0, 0, 0); __builtin_amdgcn_s_setprio(0); } while (0)
; #define PG8_WAIT_V(n) asm volatile("s_waitcnt vmcnt(" #n ")" ::: "memory")
; template <class Epi, class Sched, bool ALIGN_EPI = false, bool SP2 = false>
; __device__ __forceinline__ void gemm_phase(PG8_LAS unsigned char* lds, const Gemm g, const Sched& S, const Epi& E) {
;     ...
;             PG8_LDB(B0, 0, 0); PG8_LDB(B1, 0, 1); PG8_SCHED; PG8_LDA(At, 0, 0); PG8_STAGE(PG8_SA(1, 1), a1 + hstep, voffA);
;             PG8_WAIT_V(8); PG8_WAIT_L(0); PG8_BAR; PG8_MMA(0, 0, At, B0); PG8_MMA(0, 1, At, B1); PG8_BAR; PG8_SCHED;
;             PG8_LDA(At, 0, 1); PG8_STAGE(PG8_SB(0, 0), b2, voffB); PG8_STAGE(PG8_SB(0, 1), b2 + hstep, voffB); PG8_STAGE(PG8_SA(0, 0), a2, voffA);
;             PG8_WAIT_V(8); PG8_WAIT_L(0); PG8_BAR; PG8_MMA(1, 0, At, B0); PG8_MMA(1, 1, At, B1); PG8_BAR; PG8_SCHED;
;             PG8_LDB(B0, 1, 0); PG8_LDB(B1, 1, 1); PG8_SCHED; PG8_LDA(At, 1, 0); PG8_STAGE(PG8_SA(0, 1), a2 + hstep, voffA);
;             PG8_WAIT_V(8); PG8_WAIT_L(0); PG8_BAR; PG8_MMA(0, 0, At, B0); PG8_MMA(0, 1, At, B1); PG8_BAR; PG8_SCHED;
;             PG8_LDA(At, 1, 1); PG8_STAGE(PG8_SB(1, 0), b3, voffB); PG8_STAGE(PG8_SB(1, 1), b3 + hstep, voffB); PG8_STAGE(PG8_SA(1, 0), a3, voffA);
;             PG8_WAIT_V(8); PG8_WAIT_L(0); PG8_BAR; PG8_MMA(1, 0, At, B0); PG8_MMA(1, 1, At, B1); PG8_BAR; PG8_SCHED;
.Lkq_1_loop:
	v_add_u32_e32 v136, 0x10000, v147
	ds_read_b128 v[148:151], v136
	ds_read_b128 v[152:155], v136 offset:1024
	ds_read_b128 v[156:159], v136 offset:2048
	ds_read_b128 v[160:163], v136 offset:3072
	ds_read_b128 v[202:205], v165
	ds_read_b128 v[208:211], v165 offset:1024
	ds_read_b128 v[212:215], v165 offset:2048
	ds_read_b128 v[216:219], v165 offset:3072
	ds_read_b128 v[220:223], v165 offset:4096
	ds_read_b128 v[224:227], v165 offset:5120
	ds_read_b128 v[228:231], v165 offset:6144
	ds_read_b128 v[232:235], v165 offset:7168
	v_lshl_add_u64 v[136:137], s[76:77], 0, v[0:1]
	s_add_i32 m0, s94, 0xc000
	v_lshl_add_u64 v[144:145], s[76:77], 0, v[130:131]
	global_load_lds_dwordx4 v[136:137], off
	s_add_i32 m0, s94, 0xe000
	s_nop 0
	global_load_lds_dwordx4 v[144:145], off
	v_lshl_add_u64 v[182:183], vcc, 0, v[0:1]
	s_add_i32 m0, s93, 0x1c000
	v_lshl_add_u64 v[236:237], vcc, 0, v[130:131]
	global_load_lds_dwordx4 v[182:183], off
	s_add_i32 m0, s93, 0x1e000
	s_nop 0
	global_load_lds_dwordx4 v[236:237], off
	s_cmp_lt_u32 s82, s59
	s_cselect_b32 s83, 0x80, 0
	s_add_u32 s76, s76, s83
	s_addc_u32 s77, s77, 0
	s_add_u32 vcc_lo, vcc_lo, s83
	s_addc_u32 vcc_hi, vcc_hi, 0
	s_add_i32 s82, s82, 1
	s_waitcnt vmcnt(8)
	s_waitcnt lgkmcnt(0)
	s_barrier
	s_setprio 1
	v_mfma_f32_16x16x32_bf16 v[126:129], v[148:151], v[202:205], v[126:129]
	v_mfma_f32_16x16x32_bf16 v[122:125], v[156:159], v[202:205], v[122:125]
	v_mfma_f32_16x16x32_bf16 v[110:113], v[148:151], v[212:215], v[110:113]
	v_mfma_f32_16x16x32_bf16 v[106:109], v[156:159], v[212:215], v[106:109]
	v_mfma_f32_16x16x32_bf16 v[94:97], v[148:151], v[220:223], v[94:97]
	v_mfma_f32_16x16x32_bf16 v[90:93], v[156:159], v[220:223], v[90:93]
	v_mfma_f32_16x16x32_bf16 v[78:81], v[148:151], v[228:231], v[78:81]
	v_mfma_f32_16x16x32_bf16 v[74:77], v[156:159], v[228:231], v[74:77]
	v_mfma_f32_16x16x32_bf16 v[126:129], v[152:155], v[208:211], v[126:129]
	v_mfma_f32_16x16x32_bf16 v[122:125], v[160:163], v[208:211], v[122:125]
	v_mfma_f32_16x16x32_bf16 v[110:113], v[152:155], v[216:219], v[110:113]
	v_mfma_f32_16x16x32_bf16 v[106:109], v[160:163], v[216:219], v[106:109]
	v_mfma_f32_16x16x32_bf16 v[94:97], v[152:155], v[224:227], v[94:97]
	v_mfma_f32_16x16x32_bf16 v[90:93], v[160:163], v[224:227], v[90:93]
	v_mfma_f32_16x16x32_bf16 v[78:81], v[152:155], v[232:235], v[78:81]
	v_mfma_f32_16x16x32_bf16 v[74:77], v[160:163], v[232:235], v[74:77]
	s_setprio 0
	s_barrier
	v_add_u32_e32 v136, 0x18000, v147
	ds_read_b128 v[148:151], v136
	ds_read_b128 v[152:155], v136 offset:1024
	ds_read_b128 v[156:159], v136 offset:2048
	ds_read_b128 v[160:163], v136 offset:3072
	ds_read_b128 v[202:205], v165 offset:32768
	ds_read_b128 v[208:211], v165 offset:33792
	ds_read_b128 v[212:215], v165 offset:34816
	ds_read_b128 v[216:219], v165 offset:35840
	ds_read_b128 v[220:223], v165 offset:36864
	ds_read_b128 v[224:227], v165 offset:37888
	ds_read_b128 v[228:231], v165 offset:38912
	ds_read_b128 v[232:235], v165 offset:39936
	v_lshl_add_u64 v[136:137], s[76:77], 0, v[0:1]
	s_add_i32 m0, s94, 0x0
	v_lshl_add_u64 v[144:145], s[76:77], 0, v[130:131]
	global_load_lds_dwordx4 v[136:137], off
	s_add_i32 m0, s94, 0x2000
	s_nop 0
	global_load_lds_dwordx4 v[144:145], off
	v_lshl_add_u64 v[182:183], vcc, 0, v[0:1]
	s_add_i32 m0, s93, 0x10000
	v_lshl_add_u64 v[236:237], vcc, 0, v[130:131]
	global_load_lds_dwordx4 v[182:183], off
	s_add_i32 m0, s93, 0x12000
	s_nop 0
	global_load_lds_dwordx4 v[236:237], off
	s_cmp_lt_u32 s82, s59
	s_cselect_b32 s83, 0x80, 0
	s_add_u32 s76, s76, s83
	s_addc_u32 s77, s77, 0
	s_add_u32 vcc_lo, vcc_lo, s83
	s_addc_u32 vcc_hi, vcc_hi, 0
	s_add_i32 s82, s82, 1
	s_waitcnt vmcnt(8)
	s_waitcnt lgkmcnt(0)
	s_barrier
	s_setprio 1
	v_mfma_f32_16x16x32_bf16 v[126:129], v[148:151], v[202:205], v[126:129]
	v_mfma_f32_16x16x32_bf16 v[122:125], v[156:159], v[202:205], v[122:125]
	v_mfma_f32_16x16x32_bf16 v[110:113], v[148:151], v[212:215], v[110:113]
	v_mfma_f32_16x16x32_bf16 v[106:109], v[156:159], v[212:215], v[106:109]
	v_mfma_f32_16x16x32_bf16 v[94:97], v[148:151], v[220:223], v[94:97]
	v_mfma_f32_16x16x32_bf16 v[90:93], v[156:159], v[220:223], v[90:93]
	v_mfma_f32_16x16x32_bf16 v[78:81], v[148:151], v[228:231], v[78:81]
	v_mfma_f32_16x16x32_bf16 v[74:77], v[156:159], v[228:231], v[74:77]
	v_mfma_f32_16x16x32_bf16 v[126:129], v[152:155], v[208:211], v[126:129]
	v_mfma_f32_16x16x32_bf16 v[122:125], v[160:163], v[208:211], v[122:125]
	v_mfma_f32_16x16x32_bf16 v[110:113], v[152:155], v[216:219], v[110:113]
	v_mfma_f32_16x16x32_bf16 v[106:109], v[160:163], v[216:219], v[106:109]
	v_mfma_f32_16x16x32_bf16 v[94:97], v[152:155], v[224:227], v[94:97]
	v_mfma_f32_16x16x32_bf16 v[90:93], v[160:163], v[224:227], v[90:93]
	v_mfma_f32_16x16x32_bf16 v[78:81], v[152:155], v[232:235], v[78:81]
	v_mfma_f32_16x16x32_bf16 v[74:77], v[160:163], v[232:235], v[74:77]
	s_setprio 0
	s_barrier
	v_add_u32_e32 v136, 0x14000, v147
	ds_read_b128 v[148:151], v136
	ds_read_b128 v[152:155], v136 offset:1024
	ds_read_b128 v[156:159], v136 offset:2048
	ds_read_b128 v[160:163], v136 offset:3072
	ds_read_b128 v[202:205], v165 offset:16384
	ds_read_b128 v[208:211], v165 offset:17408
	ds_read_b128 v[212:215], v165 offset:18432
	ds_read_b128 v[216:219], v165 offset:19456
	ds_read_b128 v[220:223], v165 offset:20480
	ds_read_b128 v[224:227], v165 offset:21504
	ds_read_b128 v[228:231], v165 offset:22528
	ds_read_b128 v[232:235], v165 offset:23552
	v_lshl_add_u64 v[136:137], s[76:77], 0, v[0:1]
	s_add_i32 m0, s94, 0x8000
	v_lshl_add_u64 v[144:145], s[76:77], 0, v[130:131]
	global_load_lds_dwordx4 v[136:137], off
	s_add_i32 m0, s94, 0xa000
	s_nop 0
	global_load_lds_dwordx4 v[144:145], off
	v_lshl_add_u64 v[182:183], vcc, 0, v[0:1]
	s_add_i32 m0, s93, 0x18000
	v_lshl_add_u64 v[236:237], vcc, 0, v[130:131]
	global_load_lds_dwordx4 v[182:183], off
	s_add_i32 m0, s93, 0x1a000
	s_nop 0
	global_load_lds_dwordx4 v[236:237], off
	s_cmp_lt_u32 s82, s59
	s_cselect_b32 s83, 0x80, 0
	s_add_u32 s76, s76, s83
	s_addc_u32 s77, s77, 0
	s_add_u32 vcc_lo, vcc_lo, s83
	s_addc_u32 vcc_hi, vcc_hi, 0
	s_add_i32 s82, s82, 1
	s_waitcnt vmcnt(8)
	s_waitcnt lgkmcnt(0)
	s_barrier
; #define PG8_STAGE(bufoff, gbase, voff) do { _Pragma("unroll") for (int _i = 0; _i < 2; ++_i) \
;         __builtin_amdgcn_global_load_lds((const unsigned*)((const char*)(gbase) + (voff)[_i]), (PG8_LAS unsigned*)(lds + (bufoff) + ldsw + _i * 8192), 16, 0, 0); } while (0)
; #define PG8_LDA(dst, b, h) do { _Pragma("unroll") for (int m = 0; m < 4; ++m) _Pragma("unroll") for (int k = 0; k < 2; ++k) dst[m][k] = *(const PG8_LAS bf16x8*)(lds + PG8_SA(b, h) + aoff + m * 2048 + k * 1024); } while (0)
; #define PG8_LDB(dst, b, h) do { _Pragma("unroll") for (int n = 0; n < 2; ++n) _Pragma("unroll") for (int k = 0; k < 2; ++k) dst[n][k] = *(const PG8_LAS bf16x8*)(lds + PG8_SB(b, h) + boff + n * 2048 + k * 1024); } while (0)
; template <class Epi, class Sched, bool ALIGN_EPI = false, bool SP2 = false>
; __device__ __forceinline__ void gemm_phase(PG8_LAS unsigned char* lds, const Gemm g, const Sched& S, const Epi& E) {
;     ...
;         PG8_STAGE(PG8_SB(0, 0), cB, voffB); PG8_STAGE(PG8_SB(0, 1), cB + hstep, voffB); PG8_STAGE(PG8_SA(0, 0), cA, voffA); PG8_STAGE(PG8_SA(0, 1), cA + hstep, voffA);
;         if (wr == 1) PG8_BAR;
;         PG8_WAIT_V(2); PG8_BAR;
;         PG8_STAGE(PG8_SB(1, 0), cB + kstep, voffB); PG8_STAGE(PG8_SA(1, 0), cA + kstep, voffA); PG8_STAGE(PG8_SB(1, 1), cB + hstep + kstep, voffB);
;         PG8_WAIT_V(6); PG8_BAR;
;     ...
;             PG8_LDB(B0, 0, 0); PG8_LDB(B1, 0, 1); PG8_SCHED; PG8_LDA(At, 0, 0); PG8_STAGE(PG8_SA(1, 1), a1 + hstep, voffA);
;             PG8_WAIT_V(8); PG8_WAIT_L(0); PG8_BAR; PG8_MMA(0, 0, At, B0); PG8_MMA(0, 1, At, B1); PG8_BAR; PG8_SCHED;
;             PG8_LDA(At, 0, 1); PG8_STAGE(PG8_SB(0, 0), b2, voffB); PG8_STAGE(PG8_SB(0, 1), b2 + hstep, voffB); PG8_STAGE(PG8_SA(0, 0), a2, voffA);
;             PG8_WAIT_V(8); PG8_WAIT_L(0); PG8_BAR; PG8_MMA(1, 0, At, B0); PG8_MMA(1, 1, At, B1); PG8_BAR; PG8_SCHED;
;             PG8_LDB(B0, 1, 0); PG8_LDB(B1, 1, 1); PG8_SCHED; PG8_LDA(At, 1, 0); PG8_STAGE(PG8_SA(0, 1), a2 + hstep, voffA);
;             PG8_WAIT_V(8); PG8_WAIT_L(0); PG8_BAR; PG8_MMA(0, 0, At, B0); PG8_MMA(0, 1, At, B1); PG8_BAR; PG8_SCHED;
;             PG8_LDA(At, 1, 1); PG8_STAGE(PG8_SB(1, 0), b3, voffB); PG8_STAGE(PG8_SB(1, 1), b3 + hstep, voffB); PG8_STAGE(PG8_SA(1, 0), a3, voffA);
;             PG8_WAIT_V(8); PG8_WAIT_L(0); PG8_BAR; PG8_MMA(1, 0, At, B0); PG8_MMA(1, 1, At, B1); PG8_BAR; PG8_SCHED;
	s_setprio 1
	v_mfma_f32_16x16x32_bf16 v[126:129], v[148:151], v[202:205], v[126:129]
	v_mfma_f32_16x16x32_bf16 v[122:125], v[156:159], v[202:205], v[122:125]
	v_mfma_f32_16x16x32_bf16 v[110:113], v[148:151], v[212:215], v[110:113]
	v_mfma_f32_16x16x32_bf16 v[106:109], v[156:159], v[212:215], v[106:109]
	v_mfma_f32_16x16x32_bf16 v[94:97], v[148:151], v[220:223], v[94:97]
	v_mfma_f32_16x16x32_bf16 v[90:93], v[156:159], v[220:223], v[90:93]
	v_mfma_f32_16x16x32_bf16 v[78:81], v[148:151], v[228:231], v[78:81]
	v_mfma_f32_16x16x32_bf16 v[74:77], v[156:159], v[228:231], v[74:77]
	v_mfma_f32_16x16x32_bf16 v[126:129], v[152:155], v[208:211], v[126:129]
	v_mfma_f32_16x16x32_bf16 v[122:125], v[160:163], v[208:211], v[122:125]
	v_mfma_f32_16x16x32_bf16 v[110:113], v[152:155], v[216:219], v[110:113]
	v_mfma_f32_16x16x32_bf16 v[106:109], v[160:163], v[216:219], v[106:109]
	v_mfma_f32_16x16x32_bf16 v[94:97], v[152:155], v[224:227], v[94:97]
	v_mfma_f32_16x16x32_bf16 v[90:93], v[160:163], v[224:227], v[90:93]
	v_mfma_f32_16x16x32_bf16 v[78:81], v[152:155], v[232:235], v[78:81]
	v_mfma_f32_16x16x32_bf16 v[74:77], v[160:163], v[232:235], v[74:77]
	s_setprio 0
	s_barrier
	v_add_u32_e32 v136, 0x1c000, v147
	ds_read_b128 v[148:151], v136
	ds_read_b128 v[152:155], v136 offset:1024
	ds_read_b128 v[156:159], v136 offset:2048
	ds_read_b128 v[160:163], v136 offset:3072
	ds_read_b128 v[202:205], v165 offset:49152
	ds_read_b128 v[208:211], v165 offset:50176
	ds_read_b128 v[212:215], v165 offset:51200
	ds_read_b128 v[216:219], v165 offset:52224
	ds_read_b128 v[220:223], v165 offset:53248
	ds_read_b128 v[224:227], v165 offset:54272
	ds_read_b128 v[228:231], v165 offset:55296
	ds_read_b128 v[232:235], v165 offset:56320
	v_lshl_add_u64 v[136:137], s[76:77], 0, v[0:1]
	s_add_i32 m0, s94, 0x4000
	v_lshl_add_u64 v[144:145], s[76:77], 0, v[130:131]
	global_load_lds_dwordx4 v[136:137], off
	s_add_i32 m0, s94, 0x6000
	s_nop 0
	global_load_lds_dwordx4 v[144:145], off
	v_lshl_add_u64 v[182:183], vcc, 0, v[0:1]
	s_add_i32 m0, s93, 0x14000
	v_lshl_add_u64 v[236:237], vcc, 0, v[130:131]
	global_load_lds_dwordx4 v[182:183], off
	s_add_i32 m0, s93, 0x16000
	s_nop 0
	global_load_lds_dwordx4 v[236:237], off
	s_cmp_lt_u32 s82, s59
	s_cselect_b32 s83, 0x80, 0
	s_add_u32 s76, s76, s83
	s_addc_u32 s77, s77, 0
	s_add_u32 vcc_lo, vcc_lo, s83
	s_addc_u32 vcc_hi, vcc_hi, 0
	s_add_i32 s82, s82, 1
	s_waitcnt vmcnt(8)
	s_waitcnt lgkmcnt(0)
	s_barrier
	s_setprio 1
	v_mfma_f32_16x16x32_bf16 v[126:129], v[148:151], v[202:205], v[126:129]
	v_mfma_f32_16x16x32_bf16 v[122:125], v[156:159], v[202:205], v[122:125]
	v_mfma_f32_16x16x32_bf16 v[110:113], v[148:151], v[212:215], v[110:113]
	v_mfma_f32_16x16x32_bf16 v[106:109], v[156:159], v[212:215], v[106:109]
	v_mfma_f32_16x16x32_bf16 v[94:97], v[148:151], v[220:223], v[94:97]
	v_mfma_f32_16x16x32_bf16 v[90:93], v[156:159], v[220:223], v[90:93]
	v_mfma_f32_16x16x32_bf16 v[78:81], v[148:151], v[228:231], v[78:81]
	v_mfma_f32_16x16x32_bf16 v[74:77], v[156:159], v[228:231], v[74:77]
	v_mfma_f32_16x16x32_bf16 v[126:129], v[152:155], v[208:211], v[126:129]
	v_mfma_f32_16x16x32_bf16 v[122:125], v[160:163], v[208:211], v[122:125]
	v_mfma_f32_16x16x32_bf16 v[110:113], v[152:155], v[216:219], v[110:113]
	v_mfma_f32_16x16x32_bf16 v[106:109], v[160:163], v[216:219], v[106:109]
	v_mfma_f32_16x16x32_bf16 v[94:97], v[152:155], v[224:227], v[94:97]
	v_mfma_f32_16x16x32_bf16 v[90:93], v[160:163], v[224:227], v[90:93]
	v_mfma_f32_16x16x32_bf16 v[78:81], v[152:155], v[232:235], v[78:81]
	v_mfma_f32_16x16x32_bf16 v[74:77], v[160:163], v[232:235], v[74:77]
	s_setprio 0
	s_barrier
	s_add_i32 s83, s82, -3
	s_cmp_lt_u32 s83, s79
	s_cbranch_scc1 .Lkq_1_loop
	s_mov_b64 s[76:77], s[8:9]
	s_mov_b64 vcc, s[46:47]
	v_lshl_add_u64 v[136:137], vcc, 0, v[0:1]
	s_add_i32 m0, s93, 0x10000
	v_lshl_add_u64 v[144:145], vcc, 0, v[130:131]
	global_load_lds_dwordx4 v[136:137], off
	s_add_i32 m0, s93, 0x12000
	s_nop 0
	global_load_lds_dwordx4 v[144:145], off
	s_add_u32 vcc_lo, vcc_lo, s10
	s_addc_u32 vcc_hi, vcc_hi, 0
	v_lshl_add_u64 v[136:137], vcc, 0, v[0:1]
	s_add_i32 m0, s93, 0x14000
	v_lshl_add_u64 v[144:145], vcc, 0, v[130:131]
	global_load_lds_dwordx4 v[136:137], off
	s_add_i32 m0, s93, 0x16000
	s_nop 0
	global_load_lds_dwordx4 v[144:145], off
	v_lshl_add_u64 v[136:137], s[76:77], 0, v[0:1]
	s_add_i32 m0, s94, 0x0
	v_lshl_add_u64 v[144:145], s[76:77], 0, v[130:131]
	global_load_lds_dwordx4 v[136:137], off
	s_add_i32 m0, s94, 0x2000
	s_nop 0
	global_load_lds_dwordx4 v[144:145], off
	s_add_u32 s76, s76, s10
	s_addc_u32 s77, s77, 0
	v_lshl_add_u64 v[136:137], s[76:77], 0, v[0:1]
	s_add_i32 m0, s94, 0x4000
	v_lshl_add_u64 v[144:145], s[76:77], 0, v[130:131]
	global_load_lds_dwordx4 v[136:137], off
	s_add_i32 m0, s94, 0x6000
	s_nop 0
	global_load_lds_dwordx4 v[144:145], off
	s_add_u32 s76, s8, 0x80
	s_addc_u32 s77, s9, 0
	s_add_u32 vcc_lo, s46, 0x80
	s_addc_u32 vcc_hi, s47, 0
	v_lshl_add_u64 v[136:137], vcc, 0, v[0:1]
	s_add_i32 m0, s93, 0x18000
	v_lshl_add_u64 v[144:145], vcc, 0, v[130:131]
	global_load_lds_dwordx4 v[136:137], off
	s_add_i32 m0, s93, 0x1a000
	s_nop 0
	global_load_lds_dwordx4 v[144:145], off
	s_add_u32 vcc_lo, vcc_lo, s10
	s_addc_u32 vcc_hi, vcc_hi, 0
	v_lshl_add_u64 v[136:137], vcc, 0, v[0:1]
	s_add_i32 m0, s93, 0x1c000
	v_lshl_add_u64 v[144:145], vcc, 0, v[130:131]
	global_load_lds_dwordx4 v[136:137], off
	s_add_i32 m0, s93, 0x1e000
	s_nop 0
	global_load_lds_dwordx4 v[144:145], off
	v_lshl_add_u64 v[136:137], s[76:77], 0, v[0:1]
	s_add_i32 m0, s94, 0x8000
	v_lshl_add_u64 v[144:145], s[76:77], 0, v[130:131]
	global_load_lds_dwordx4 v[136:137], off
	s_add_i32 m0, s94, 0xa000
	s_nop 0
	global_load_lds_dwordx4 v[144:145], off
	s_branch .Lkq_exit
	s_nop 0

; #define PG8_STAGE(bufoff, gbase, voff) do { _Pragma("unroll") for (int _i = 0; _i < 2; ++_i) \
;         __builtin_amdgcn_global_load_lds((const unsigned*)((const char*)(gbase) + (voff)[_i]), (PG8_LAS unsigned*)(lds + (bufoff) + ldsw + _i * 8192), 16, 0, 0); } while (0)
; #define PG8_LDA(dst, b, h) do { _Pragma("unroll") for (int m = 0; m < 4; ++m) _Pragma("unroll") for (int k = 0; k < 2; ++k) dst[m][k] = *(const PG8_LAS bf16x8*)(lds + PG8_SA(b, h) + aoff + m * 2048 + k * 1024); } while (0)
; #define PG8_LDB(dst, b, h) do { _Pragma("unroll") for (int n = 0; n < 2; ++n) _Pragma("unroll") for (int k = 0; k < 2; ++k) dst[n][k] = *(const PG8_LAS bf16x8*)(lds + PG8_SB(b, h) + boff + n * 2048 + k * 1024); } while (0)
; #define PG8_MMA(ai, bj, At, Bt) do { __builtin_amdgcn_s_setprio(1); _Pragma("unroll") for (int m = 0; m < 4; ++m) _Pragma("unroll") for (int n = 0; n < 2; ++n) _Pragma("unroll") for (int k = 0; k < 2; ++k) \
;         acc[ai][bj][m][n] = __builtin_amdgcn_mfma_f32_16x16x32_bf16(Bt[n][k], At[m][k], acc[ai][bj][m][n], 0, 0, 0); __builtin_amdgcn_s_setprio(0); } while (0)
; #define PG8_WAIT_V(n) asm volatile("s_waitcnt vmcnt(" #n ")" ::: "memory")
; template <class Epi, class Sched, bool ALIGN_EPI = false, bool SP2 = false>
; __device__ __forceinline__ void gemm_phase(PG8_LAS unsigned char* lds, const Gemm g, const Sched& S, const Epi& E) {
;     ...
;             PG8_LDB(B0, 0, 0); PG8_LDB(B1, 0, 1); PG8_SCHED; PG8_LDA(At, 0, 0); PG8_STAGE(PG8_SA(1, 1), a1 + hstep, voffA);
;             PG8_WAIT_V(8); PG8_WAIT_L(0); PG8_BAR; PG8_MMA(0, 0, At, B0); PG8_MMA(0, 1, At, B1); PG8_BAR; PG8_SCHED;
;             PG8_LDA(At, 0, 1); PG8_STAGE(PG8_SB(0, 0), b2, voffB); PG8_STAGE(PG8_SB(0, 1), b2 + hstep, voffB); PG8_STAGE(PG8_SA(0, 0), a2, voffA);
;             PG8_WAIT_V(8); PG8_WAIT_L(0); PG8_BAR; PG8_MMA(1, 0, At, B0); PG8_MMA(1, 1, At, B1); PG8_BAR; PG8_SCHED;
;             PG8_LDB(B0, 1, 0); PG8_LDB(B1, 1, 1); PG8_SCHED; PG8_LDA(At, 1, 0); PG8_STAGE(PG8_SA(0, 1), a2 + hstep, voffA);
;             PG8_WAIT_V(8); PG8_WAIT_L(0); PG8_BAR; PG8_MMA(0, 0, At, B0); PG8_MMA(0, 1, At, B1); PG8_BAR; PG8_SCHED;
;             PG8_LDA(At, 1, 1); PG8_STAGE(PG8_SB(1, 0), b3, voffB); PG8_STAGE(PG8_SB(1, 1), b3 + hstep, voffB); PG8_STAGE(PG8_SA(1, 0), a3, voffA);
;             PG8_WAIT_V(8); PG8_WAIT_L(0); PG8_BAR; PG8_MMA(1, 0, At, B0); PG8_MMA(1, 1, At, B1); PG8_BAR; PG8_SCHED;
.Lkq_2_loop:
	v_add_u32_e32 v136, 0x10000, v147
	ds_read_b128 v[148:151], v136
	ds_read_b128 v[152:155], v136 offset:1024
	ds_read_b128 v[156:159], v136 offset:2048
	ds_read_b128 v[160:163], v136 offset:3072
	ds_read_b128 v[202:205], v165 offset:16384
	ds_read_b128 v[208:211], v165 offset:17408
	ds_read_b128 v[212:215], v165 offset:18432
	ds_read_b128 v[216:219], v165 offset:19456
	ds_read_b128 v[220:223], v165 offset:20480
	ds_read_b128 v[224:227], v165 offset:21504
	ds_read_b128 v[228:231], v165 offset:22528
	ds_read_b128 v[232:235], v165 offset:23552
	v_lshl_add_u64 v[136:137], s[76:77], 0, v[0:1]
	s_add_i32 m0, s94, 0x8000
	v_lshl_add_u64 v[144:145], s[76:77], 0, v[130:131]
	global_load_lds_dwordx4 v[136:137], off
	s_add_i32 m0, s94, 0xa000
	s_nop 0
	global_load_lds_dwordx4 v[144:145], off
	v_lshl_add_u64 v[182:183], vcc, 0, v[0:1]
	s_add_i32 m0, s93, 0x1c000
	v_lshl_add_u64 v[236:237], vcc, 0, v[130:131]
	global_load_lds_dwordx4 v[182:183], off
	s_add_i32 m0, s93, 0x1e000
	s_nop 0
	global_load_lds_dwordx4 v[236:237], off
	s_cmp_lt_u32 s82, s59
	s_cselect_b32 s83, 0x80, 0
	s_add_u32 s76, s76, s83
	s_addc_u32 s77, s77, 0
	s_add_u32 vcc_lo, vcc_lo, s83
	s_addc_u32 vcc_hi, vcc_hi, 0
	s_add_i32 s82, s82, 1
	s_waitcnt vmcnt(8)
	s_waitcnt lgkmcnt(0)
	s_barrier
	s_setprio 1
	v_mfma_f32_16x16x32_bf16 v[62:65], v[148:151], v[202:205], v[62:65]
	v_mfma_f32_16x16x32_bf16 v[58:61], v[156:159], v[202:205], v[58:61]
	v_mfma_f32_16x16x32_bf16 v[46:49], v[148:151], v[212:215], v[46:49]
	v_mfma_f32_16x16x32_bf16 v[42:45], v[156:159], v[212:215], v[42:45]
	v_mfma_f32_16x16x32_bf16 v[30:33], v[148:151], v[220:223], v[30:33]
	v_mfma_f32_16x16x32_bf16 v[26:29], v[156:159], v[220:223], v[26:29]
	v_mfma_f32_16x16x32_bf16 v[14:17], v[148:151], v[228:231], v[14:17]
	v_mfma_f32_16x16x32_bf16 v[10:13], v[156:159], v[228:231], v[10:13]
	v_mfma_f32_16x16x32_bf16 v[62:65], v[152:155], v[208:211], v[62:65]
	v_mfma_f32_16x16x32_bf16 v[58:61], v[160:163], v[208:211], v[58:61]
	v_mfma_f32_16x16x32_bf16 v[46:49], v[152:155], v[216:219], v[46:49]
	v_mfma_f32_16x16x32_bf16 v[42:45], v[160:163], v[216:219], v[42:45]
	v_mfma_f32_16x16x32_bf16 v[30:33], v[152:155], v[224:227], v[30:33]
	v_mfma_f32_16x16x32_bf16 v[26:29], v[160:163], v[224:227], v[26:29]
	v_mfma_f32_16x16x32_bf16 v[14:17], v[152:155], v[232:235], v[14:17]
	v_mfma_f32_16x16x32_bf16 v[10:13], v[160:163], v[232:235], v[10:13]
	s_setprio 0
	s_barrier
	v_add_u32_e32 v136, 0x18000, v147
	ds_read_b128 v[148:151], v136
	ds_read_b128 v[152:155], v136 offset:1024
	ds_read_b128 v[156:159], v136 offset:2048
	ds_read_b128 v[160:163], v136 offset:3072
	ds_read_b128 v[202:205], v165 offset:49152
	ds_read_b128 v[208:211], v165 offset:50176
	ds_read_b128 v[212:215], v165 offset:51200
	ds_read_b128 v[216:219], v165 offset:52224
	ds_read_b128 v[220:223], v165 offset:53248
	ds_read_b128 v[224:227], v165 offset:54272
	ds_read_b128 v[228:231], v165 offset:55296
	ds_read_b128 v[232:235], v165 offset:56320
	v_lshl_add_u64 v[136:137], s[76:77], 0, v[0:1]
	s_add_i32 m0, s94, 0x4000
	v_lshl_add_u64 v[144:145], s[76:77], 0, v[130:131]
	global_load_lds_dwordx4 v[136:137], off
	s_add_i32 m0, s94, 0x6000
	s_nop 0
	global_load_lds_dwordx4 v[144:145], off
	v_lshl_add_u64 v[182:183], vcc, 0, v[0:1]
	s_add_i32 m0, s93, 0x10000
	v_lshl_add_u64 v[236:237], vcc, 0, v[130:131]
	global_load_lds_dwordx4 v[182:183], off
	s_add_i32 m0, s93, 0x12000
	s_nop 0
	global_load_lds_dwordx4 v[236:237], off
	s_cmp_lt_u32 s82, s59
	s_cselect_b32 s83, 0x80, 0
	s_add_u32 s76, s76, s83
	s_addc_u32 s77, s77, 0
	s_add_u32 vcc_lo, vcc_lo, s83
	s_addc_u32 vcc_hi, vcc_hi, 0
	s_add_i32 s82, s82, 1
	s_waitcnt vmcnt(8)
	s_waitcnt lgkmcnt(0)
	s_barrier
	s_setprio 1
	v_mfma_f32_16x16x32_bf16 v[62:65], v[148:151], v[202:205], v[62:65]
	v_mfma_f32_16x16x32_bf16 v[58:61], v[156:159], v[202:205], v[58:61]
	v_mfma_f32_16x16x32_bf16 v[46:49], v[148:151], v[212:215], v[46:49]
	v_mfma_f32_16x16x32_bf16 v[42:45], v[156:159], v[212:215], v[42:45]
	v_mfma_f32_16x16x32_bf16 v[30:33], v[148:151], v[220:223], v[30:33]
	v_mfma_f32_16x16x32_bf16 v[26:29], v[156:159], v[220:223], v[26:29]
	v_mfma_f32_16x16x32_bf16 v[14:17], v[148:151], v[228:231], v[14:17]
	v_mfma_f32_16x16x32_bf16 v[10:13], v[156:159], v[228:231], v[10:13]
	v_mfma_f32_16x16x32_bf16 v[62:65], v[152:155], v[208:211], v[62:65]
	v_mfma_f32_16x16x32_bf16 v[58:61], v[160:163], v[208:211], v[58:61]
	v_mfma_f32_16x16x32_bf16 v[46:49], v[152:155], v[216:219], v[46:49]
	v_mfma_f32_16x16x32_bf16 v[42:45], v[160:163], v[216:219], v[42:45]
	v_mfma_f32_16x16x32_bf16 v[30:33], v[152:155], v[224:227], v[30:33]
	v_mfma_f32_16x16x32_bf16 v[26:29], v[160:163], v[224:227], v[26:29]
	v_mfma_f32_16x16x32_bf16 v[14:17], v[152:155], v[232:235], v[14:17]
	v_mfma_f32_16x16x32_bf16 v[10:13], v[160:163], v[232:235], v[10:13]
	s_setprio 0
	s_barrier
	v_add_u32_e32 v136, 0x14000, v147
	ds_read_b128 v[148:151], v136
	ds_read_b128 v[152:155], v136 offset:1024
	ds_read_b128 v[156:159], v136 offset:2048
	ds_read_b128 v[160:163], v136 offset:3072
	ds_read_b128 v[202:205], v165
	ds_read_b128 v[208:211], v165 offset:1024
	ds_read_b128 v[212:215], v165 offset:2048
	ds_read_b128 v[216:219], v165 offset:3072
	ds_read_b128 v[220:223], v165 offset:4096
	ds_read_b128 v[224:227], v165 offset:5120
	ds_read_b128 v[228:231], v165 offset:6144
	ds_read_b128 v[232:235], v165 offset:7168
	v_lshl_add_u64 v[136:137], s[76:77], 0, v[0:1]
	s_add_i32 m0, s94, 0xc000
	v_lshl_add_u64 v[144:145], s[76:77], 0, v[130:131]
	global_load_lds_dwordx4 v[136:137], off
	s_add_i32 m0, s94, 0xe000
	s_nop 0
	global_load_lds_dwordx4 v[144:145], off
	v_lshl_add_u64 v[182:183], vcc, 0, v[0:1]
	s_add_i32 m0, s93, 0x18000
	v_lshl_add_u64 v[236:237], vcc, 0, v[130:131]
	global_load_lds_dwordx4 v[182:183], off
	s_add_i32 m0, s93, 0x1a000
	s_nop 0
	global_load_lds_dwordx4 v[236:237], off
	s_cmp_lt_u32 s82, s59
	s_cselect_b32 s83, 0x80, 0
	s_add_u32 s76, s76, s83
	s_addc_u32 s77, s77, 0
	s_add_u32 vcc_lo, vcc_lo, s83
	s_addc_u32 vcc_hi, vcc_hi, 0
	s_add_i32 s82, s82, 1
	s_waitcnt vmcnt(8)
	s_waitcnt lgkmcnt(0)
	s_barrier
; #define PG8_STAGE(bufoff, gbase, voff) do { _Pragma("unroll") for (int _i = 0; _i < 2; ++_i) \
;         __builtin_amdgcn_global_load_lds((const unsigned*)((const char*)(gbase) + (voff)[_i]), (PG8_LAS unsigned*)(lds + (bufoff) + ldsw + _i * 8192), 16, 0, 0); } while (0)
; #define PG8_LDA(dst, b, h) do { _Pragma("unroll") for (int m = 0; m < 4; ++m) _Pragma("unroll") for (int k = 0; k < 2; ++k) dst[m][k] = *(const PG8_LAS bf16x8*)(lds + PG8_SA(b, h) + aoff + m * 2048 + k * 1024); } while (0)
; #define PG8_LDB(dst, b, h) do { _Pragma("unroll") for (int n = 0; n < 2; ++n) _Pragma("unroll") for (int k = 0; k < 2; ++k) dst[n][k] = *(const PG8_LAS bf16x8*)(lds + PG8_SB(b, h) + boff + n * 2048 + k * 1024); } while (0)
; template <class Epi, class Sched, bool ALIGN_EPI = false, bool SP2 = false>
; __device__ __forceinline__ void gemm_phase(PG8_LAS unsigned char* lds, const Gemm g, const Sched& S, const Epi& E) {
;     ...
;         PG8_STAGE(PG8_SB(0, 0), cB, voffB); PG8_STAGE(PG8_SB(0, 1), cB + hstep, voffB); PG8_STAGE(PG8_SA(0, 0), cA, voffA); PG8_STAGE(PG8_SA(0, 1), cA + hstep, voffA);
;         if (wr == 1) PG8_BAR;
;         PG8_WAIT_V(2); PG8_BAR;
;         PG8_STAGE(PG8_SB(1, 0), cB + kstep, voffB); PG8_STAGE(PG8_SA(1, 0), cA + kstep, voffA); PG8_STAGE(PG8_SB(1, 1), cB + hstep + kstep, voffB);
;         PG8_WAIT_V(6); PG8_BAR;
;     ...
;             PG8_LDB(B0, 0, 0); PG8_LDB(B1, 0, 1); PG8_SCHED; PG8_LDA(At, 0, 0); PG8_STAGE(PG8_SA(1, 1), a1 + hstep, voffA);
;             PG8_WAIT_V(8); PG8_WAIT_L(0); PG8_BAR; PG8_MMA(0, 0, At, B0); PG8_MMA(0, 1, At, B1); PG8_BAR; PG8_SCHED;
;             PG8_LDA(At, 0, 1); PG8_STAGE(PG8_SB(0, 0), b2, voffB); PG8_STAGE(PG8_SB(0, 1), b2 + hstep, voffB); PG8_STAGE(PG8_SA(0, 0), a2, voffA);
;             PG8_WAIT_V(8); PG8_WAIT_L(0); PG8_BAR; PG8_MMA(1, 0, At, B0); PG8_MMA(1, 1, At, B1); PG8_BAR; PG8_SCHED;
;             PG8_LDB(B0, 1, 0); PG8_LDB(B1, 1, 1); PG8_SCHED; PG8_LDA(At, 1, 0); PG8_STAGE(PG8_SA(0, 1), a2 + hstep, voffA);
;             PG8_WAIT_V(8); PG8_WAIT_L(0); PG8_BAR; PG8_MMA(0, 0, At, B0); PG8_MMA(0, 1, At, B1); PG8_BAR; PG8_SCHED;
;             PG8_LDA(At, 1, 1); PG8_STAGE(PG8_SB(1, 0), b3, voffB); PG8_STAGE(PG8_SB(1, 1), b3 + hstep, voffB); PG8_STAGE(PG8_SA(1, 0), a3, voffA);
;             PG8_WAIT_V(8); PG8_WAIT_L(0); PG8_BAR; PG8_MMA(1, 0, At, B0); PG8_MMA(1, 1, At, B1); PG8_BAR; PG8_SCHED;
	s_setprio 1
	v_mfma_f32_16x16x32_bf16 v[62:65], v[148:151], v[202:205], v[62:65]
	v_mfma_f32_16x16x32_bf16 v[58:61], v[156:159], v[202:205], v[58:61]
	v_mfma_f32_16x16x32_bf16 v[46:49], v[148:151], v[212:215], v[46:49]
	v_mfma_f32_16x16x32_bf16 v[42:45], v[156:159], v[212:215], v[42:45]
	v_mfma_f32_16x16x32_bf16 v[30:33], v[148:151], v[220:223], v[30:33]
	v_mfma_f32_16x16x32_bf16 v[26:29], v[156:159], v[220:223], v[26:29]
	v_mfma_f32_16x16x32_bf16 v[14:17], v[148:151], v[228:231], v[14:17]
	v_mfma_f32_16x16x32_bf16 v[10:13], v[156:159], v[228:231], v[10:13]
	v_mfma_f32_16x16x32_bf16 v[62:65], v[152:155], v[208:211], v[62:65]
	v_mfma_f32_16x16x32_bf16 v[58:61], v[160:163], v[208:211], v[58:61]
	v_mfma_f32_16x16x32_bf16 v[46:49], v[152:155], v[216:219], v[46:49]
	v_mfma_f32_16x16x32_bf16 v[42:45], v[160:163], v[216:219], v[42:45]
	v_mfma_f32_16x16x32_bf16 v[30:33], v[152:155], v[224:227], v[30:33]
	v_mfma_f32_16x16x32_bf16 v[26:29], v[160:163], v[224:227], v[26:29]
	v_mfma_f32_16x16x32_bf16 v[14:17], v[152:155], v[232:235], v[14:17]
	v_mfma_f32_16x16x32_bf16 v[10:13], v[160:163], v[232:235], v[10:13]
	s_setprio 0
	s_barrier
	v_add_u32_e32 v136, 0x1c000, v147
	ds_read_b128 v[148:151], v136
	ds_read_b128 v[152:155], v136 offset:1024
	ds_read_b128 v[156:159], v136 offset:2048
	ds_read_b128 v[160:163], v136 offset:3072
	ds_read_b128 v[202:205], v165 offset:32768
	ds_read_b128 v[208:211], v165 offset:33792
	ds_read_b128 v[212:215], v165 offset:34816
	ds_read_b128 v[216:219], v165 offset:35840
	ds_read_b128 v[220:223], v165 offset:36864
	ds_read_b128 v[224:227], v165 offset:37888
	ds_read_b128 v[228:231], v165 offset:38912
	ds_read_b128 v[232:235], v165 offset:39936
	v_lshl_add_u64 v[136:137], s[76:77], 0, v[0:1]
	s_add_i32 m0, s94, 0x0
	v_lshl_add_u64 v[144:145], s[76:77], 0, v[130:131]
	global_load_lds_dwordx4 v[136:137], off
	s_add_i32 m0, s94, 0x2000
	s_nop 0
	global_load_lds_dwordx4 v[144:145], off
	v_lshl_add_u64 v[182:183], vcc, 0, v[0:1]
	s_add_i32 m0, s93, 0x14000
	v_lshl_add_u64 v[236:237], vcc, 0, v[130:131]
	global_load_lds_dwordx4 v[182:183], off
	s_add_i32 m0, s93, 0x16000
	s_nop 0
	global_load_lds_dwordx4 v[236:237], off
	s_cmp_lt_u32 s82, s59
	s_cselect_b32 s83, 0x80, 0
	s_add_u32 s76, s76, s83
	s_addc_u32 s77, s77, 0
	s_add_u32 vcc_lo, vcc_lo, s83
	s_addc_u32 vcc_hi, vcc_hi, 0
	s_add_i32 s82, s82, 1
	s_waitcnt vmcnt(8)
	s_waitcnt lgkmcnt(0)
	s_barrier
	s_setprio 1
	v_mfma_f32_16x16x32_bf16 v[62:65], v[148:151], v[202:205], v[62:65]
	v_mfma_f32_16x16x32_bf16 v[58:61], v[156:159], v[202:205], v[58:61]
	v_mfma_f32_16x16x32_bf16 v[46:49], v[148:151], v[212:215], v[46:49]
	v_mfma_f32_16x16x32_bf16 v[42:45], v[156:159], v[212:215], v[42:45]
	v_mfma_f32_16x16x32_bf16 v[30:33], v[148:151], v[220:223], v[30:33]
	v_mfma_f32_16x16x32_bf16 v[26:29], v[156:159], v[220:223], v[26:29]
	v_mfma_f32_16x16x32_bf16 v[14:17], v[148:151], v[228:231], v[14:17]
	v_mfma_f32_16x16x32_bf16 v[10:13], v[156:159], v[228:231], v[10:13]
	v_mfma_f32_16x16x32_bf16 v[62:65], v[152:155], v[208:211], v[62:65]
	v_mfma_f32_16x16x32_bf16 v[58:61], v[160:163], v[208:211], v[58:61]
	v_mfma_f32_16x16x32_bf16 v[46:49], v[152:155], v[216:219], v[46:49]
	v_mfma_f32_16x16x32_bf16 v[42:45], v[160:163], v[216:219], v[42:45]
	v_mfma_f32_16x16x32_bf16 v[30:33], v[152:155], v[224:227], v[30:33]
	v_mfma_f32_16x16x32_bf16 v[26:29], v[160:163], v[224:227], v[26:29]
	v_mfma_f32_16x16x32_bf16 v[14:17], v[152:155], v[232:235], v[14:17]
	v_mfma_f32_16x16x32_bf16 v[10:13], v[160:163], v[232:235], v[10:13]
	s_setprio 0
	s_barrier
	s_add_i32 s83, s82, -3
	s_cmp_lt_u32 s83, s79
	s_cbranch_scc1 .Lkq_2_loop
	s_mov_b64 s[76:77], s[8:9]
	s_mov_b64 vcc, s[46:47]
	v_lshl_add_u64 v[136:137], vcc, 0, v[0:1]
	s_add_i32 m0, s93, 0x10000
	v_lshl_add_u64 v[144:145], vcc, 0, v[130:131]
	global_load_lds_dwordx4 v[136:137], off
	s_add_i32 m0, s93, 0x12000
	s_nop 0
	global_load_lds_dwordx4 v[144:145], off
	s_add_u32 vcc_lo, vcc_lo, s10
	s_addc_u32 vcc_hi, vcc_hi, 0
	v_lshl_add_u64 v[136:137], vcc, 0, v[0:1]
	s_add_i32 m0, s93, 0x14000
	v_lshl_add_u64 v[144:145], vcc, 0, v[130:131]
	global_load_lds_dwordx4 v[136:137], off
	s_add_i32 m0, s93, 0x16000
	s_nop 0
	global_load_lds_dwordx4 v[144:145], off
	v_lshl_add_u64 v[136:137], s[76:77], 0, v[0:1]
	s_add_i32 m0, s94, 0x0
	v_lshl_add_u64 v[144:145], s[76:77], 0, v[130:131]
	global_load_lds_dwordx4 v[136:137], off
	s_add_i32 m0, s94, 0x2000
	s_nop 0
	global_load_lds_dwordx4 v[144:145], off
	s_add_u32 s76, s76, s10
	s_addc_u32 s77, s77, 0
	v_lshl_add_u64 v[136:137], s[76:77], 0, v[0:1]
	s_add_i32 m0, s94, 0x4000
	v_lshl_add_u64 v[144:145], s[76:77], 0, v[130:131]
	global_load_lds_dwordx4 v[136:137], off
	s_add_i32 m0, s94, 0x6000
	s_nop 0
	global_load_lds_dwordx4 v[144:145], off
	s_add_u32 s76, s8, 0x80
	s_addc_u32 s77, s9, 0
	s_add_u32 vcc_lo, s46, 0x80
	s_addc_u32 vcc_hi, s47, 0
	v_lshl_add_u64 v[136:137], vcc, 0, v[0:1]
	s_add_i32 m0, s93, 0x18000
	v_lshl_add_u64 v[144:145], vcc, 0, v[130:131]
	global_load_lds_dwordx4 v[136:137], off
	s_add_i32 m0, s93, 0x1a000
	s_nop 0
	global_load_lds_dwordx4 v[144:145], off
	s_add_u32 vcc_lo, vcc_lo, s10
	s_addc_u32 vcc_hi, vcc_hi, 0
	v_lshl_add_u64 v[136:137], vcc, 0, v[0:1]
	s_add_i32 m0, s93, 0x1c000
	v_lshl_add_u64 v[144:145], vcc, 0, v[130:131]
	global_load_lds_dwordx4 v[136:137], off
	s_add_i32 m0, s93, 0x1e000
	s_nop 0
	global_load_lds_dwordx4 v[144:145], off
	v_lshl_add_u64 v[136:137], s[76:77], 0, v[0:1]
	s_add_i32 m0, s94, 0x8000
	v_lshl_add_u64 v[144:145], s[76:77], 0, v[130:131]
	global_load_lds_dwordx4 v[136:137], off
	s_add_i32 m0, s94, 0xa000
	s_nop 0
	global_load_lds_dwordx4 v[144:145], off
	s_branch .Lkq_exit
	s_nop 0
	s_nop 0
	s_nop 0
	s_nop 0
	s_nop 0
	s_nop 0
	s_nop 0
	s_nop 0
	s_nop 0
	s_nop 0
	s_nop 0
	s_nop 0
	s_nop 0
	s_nop 0
	s_nop 0

; #define PG8_STAGE(bufoff, gbase, voff) do { _Pragma("unroll") for (int _i = 0; _i < 2; ++_i) \
;         __builtin_amdgcn_global_load_lds((const unsigned*)((const char*)(gbase) + (voff)[_i]), (PG8_LAS unsigned*)(lds + (bufoff) + ldsw + _i * 8192), 16, 0, 0); } while (0)
; #define PG8_LDA(dst, b, h) do { _Pragma("unroll") for (int m = 0; m < 4; ++m) _Pragma("unroll") for (int k = 0; k < 2; ++k) dst[m][k] = *(const PG8_LAS bf16x8*)(lds + PG8_SA(b, h) + aoff + m * 2048 + k * 1024); } while (0)
; #define PG8_LDB(dst, b, h) do { _Pragma("unroll") for (int n = 0; n < 2; ++n) _Pragma("unroll") for (int k = 0; k < 2; ++k) dst[n][k] = *(const PG8_LAS bf16x8*)(lds + PG8_SB(b, h) + boff + n * 2048 + k * 1024); } while (0)
; #define PG8_MMA(ai, bj, At, Bt) do { __builtin_amdgcn_s_setprio(1); _Pragma("unroll") for (int m = 0; m < 4; ++m) _Pragma("unroll") for (int n = 0; n < 2; ++n) _Pragma("unroll") for (int k = 0; k < 2; ++k) \
;         acc[ai][bj][m][n] = __builtin_amdgcn_mfma_f32_16x16x32_bf16(Bt[n][k], At[m][k], acc[ai][bj][m][n], 0, 0, 0); __builtin_amdgcn_s_setprio(0); } while (0)
; #define PG8_WAIT_V(n) asm volatile("s_waitcnt vmcnt(" #n ")" ::: "memory")
; template <class Epi, class Sched, bool ALIGN_EPI = false, bool SP2 = false>
; __device__ __forceinline__ void gemm_phase(PG8_LAS unsigned char* lds, const Gemm g, const Sched& S, const Epi& E) {
;     ...
;             PG8_LDB(B0, 0, 0); PG8_LDB(B1, 0, 1); PG8_SCHED; PG8_LDA(At, 0, 0); PG8_STAGE(PG8_SA(1, 1), a1 + hstep, voffA);
;             PG8_WAIT_V(8); PG8_WAIT_L(0); PG8_BAR; PG8_MMA(0, 0, At, B0); PG8_MMA(0, 1, At, B1); PG8_BAR; PG8_SCHED;
;             PG8_LDA(At, 0, 1); PG8_STAGE(PG8_SB(0, 0), b2, voffB); PG8_STAGE(PG8_SB(0, 1), b2 + hstep, voffB); PG8_STAGE(PG8_SA(0, 0), a2, voffA);
;             PG8_WAIT_V(8); PG8_WAIT_L(0); PG8_BAR; PG8_MMA(1, 0, At, B0); PG8_MMA(1, 1, At, B1); PG8_BAR; PG8_SCHED;
;             PG8_LDB(B0, 1, 0); PG8_LDB(B1, 1, 1); PG8_SCHED; PG8_LDA(At, 1, 0); PG8_STAGE(PG8_SA(0, 1), a2 + hstep, voffA);
;             PG8_WAIT_V(8); PG8_WAIT_L(0); PG8_BAR; PG8_MMA(0, 0, At, B0); PG8_MMA(0, 1, At, B1); PG8_BAR; PG8_SCHED;
;             PG8_LDA(At, 1, 1); PG8_STAGE(PG8_SB(1, 0), b3, voffB); PG8_STAGE(PG8_SB(1, 1), b3 + hstep, voffB); PG8_STAGE(PG8_SA(1, 0), a3, voffA);
;             PG8_WAIT_V(8); PG8_WAIT_L(0); PG8_BAR; PG8_MMA(1, 0, At, B0); PG8_MMA(1, 1, At, B1); PG8_BAR; PG8_SCHED;
.Lkq_3_loop:
	v_add_u32_e32 v136, 0x14000, v147
	ds_read_b128 v[166:169], v136
	ds_read_b128 v[170:173], v136 offset:1024
	ds_read_b128 v[174:177], v136 offset:2048
	ds_read_b128 v[178:181], v136 offset:3072
	ds_read_b128 v[202:205], v165
	ds_read_b128 v[208:211], v165 offset:1024
	ds_read_b128 v[212:215], v165 offset:2048
	ds_read_b128 v[216:219], v165 offset:3072
	ds_read_b128 v[220:223], v165 offset:4096
	ds_read_b128 v[224:227], v165 offset:5120
	ds_read_b128 v[228:231], v165 offset:6144
	ds_read_b128 v[232:235], v165 offset:7168
	v_lshl_add_u64 v[136:137], s[76:77], 0, v[0:1]
	s_add_i32 m0, s94, 0xc000
	v_lshl_add_u64 v[144:145], s[76:77], 0, v[130:131]
	global_load_lds_dwordx4 v[136:137], off
	s_add_i32 m0, s94, 0xe000
	s_nop 0
	global_load_lds_dwordx4 v[144:145], off
	v_lshl_add_u64 v[182:183], vcc, 0, v[0:1]
	s_add_i32 m0, s93, 0x18000
	v_lshl_add_u64 v[236:237], vcc, 0, v[130:131]
	global_load_lds_dwordx4 v[182:183], off
	s_add_i32 m0, s93, 0x1a000
	s_nop 0
	global_load_lds_dwordx4 v[236:237], off
	s_cmp_lt_u32 s82, s59
	s_cselect_b32 s83, 0x80, 0
	s_add_u32 s76, s76, s83
	s_addc_u32 s77, s77, 0
	s_add_u32 vcc_lo, vcc_lo, s83
	s_addc_u32 vcc_hi, vcc_hi, 0
	s_add_i32 s82, s82, 1
	s_waitcnt vmcnt(8)
	s_waitcnt lgkmcnt(0)
	s_barrier
	s_setprio 1
	v_mfma_f32_16x16x32_bf16 v[118:121], v[166:169], v[202:205], v[118:121]
	v_mfma_f32_16x16x32_bf16 v[114:117], v[174:177], v[202:205], v[114:117]
	v_mfma_f32_16x16x32_bf16 v[102:105], v[166:169], v[212:215], v[102:105]
	v_mfma_f32_16x16x32_bf16 v[98:101], v[174:177], v[212:215], v[98:101]
	v_mfma_f32_16x16x32_bf16 v[86:89], v[166:169], v[220:223], v[86:89]
	v_mfma_f32_16x16x32_bf16 v[82:85], v[174:177], v[220:223], v[82:85]
	v_mfma_f32_16x16x32_bf16 v[70:73], v[166:169], v[228:231], v[70:73]
	v_mfma_f32_16x16x32_bf16 v[66:69], v[174:177], v[228:231], v[66:69]
	v_mfma_f32_16x16x32_bf16 v[118:121], v[170:173], v[208:211], v[118:121]
	v_mfma_f32_16x16x32_bf16 v[114:117], v[178:181], v[208:211], v[114:117]
	v_mfma_f32_16x16x32_bf16 v[102:105], v[170:173], v[216:219], v[102:105]
	v_mfma_f32_16x16x32_bf16 v[98:101], v[178:181], v[216:219], v[98:101]
	v_mfma_f32_16x16x32_bf16 v[86:89], v[170:173], v[224:227], v[86:89]
	v_mfma_f32_16x16x32_bf16 v[82:85], v[178:181], v[224:227], v[82:85]
	v_mfma_f32_16x16x32_bf16 v[70:73], v[170:173], v[232:235], v[70:73]
	v_mfma_f32_16x16x32_bf16 v[66:69], v[178:181], v[232:235], v[66:69]
	s_setprio 0
	s_barrier
	v_add_u32_e32 v136, 0x1c000, v147
	ds_read_b128 v[166:169], v136
	ds_read_b128 v[170:173], v136 offset:1024
	ds_read_b128 v[174:177], v136 offset:2048
	ds_read_b128 v[178:181], v136 offset:3072
	ds_read_b128 v[202:205], v165 offset:32768
	ds_read_b128 v[208:211], v165 offset:33792
	ds_read_b128 v[212:215], v165 offset:34816
	ds_read_b128 v[216:219], v165 offset:35840
	ds_read_b128 v[220:223], v165 offset:36864
	ds_read_b128 v[224:227], v165 offset:37888
	ds_read_b128 v[228:231], v165 offset:38912
	ds_read_b128 v[232:235], v165 offset:39936
	v_lshl_add_u64 v[136:137], s[76:77], 0, v[0:1]
	s_add_i32 m0, s94, 0x0
	v_lshl_add_u64 v[144:145], s[76:77], 0, v[130:131]
	global_load_lds_dwordx4 v[136:137], off
	s_add_i32 m0, s94, 0x2000
	s_nop 0
	global_load_lds_dwordx4 v[144:145], off
	v_lshl_add_u64 v[182:183], vcc, 0, v[0:1]
	s_add_i32 m0, s93, 0x14000
	v_lshl_add_u64 v[236:237], vcc, 0, v[130:131]
	global_load_lds_dwordx4 v[182:183], off
	s_add_i32 m0, s93, 0x16000
	s_nop 0
	global_load_lds_dwordx4 v[236:237], off
	s_cmp_lt_u32 s82, s59
	s_cselect_b32 s83, 0x80, 0
	s_add_u32 s76, s76, s83
	s_addc_u32 s77, s77, 0
	s_add_u32 vcc_lo, vcc_lo, s83
	s_addc_u32 vcc_hi, vcc_hi, 0
	s_add_i32 s82, s82, 1
	s_waitcnt vmcnt(8)
	s_waitcnt lgkmcnt(0)
	s_barrier
	s_setprio 1
	v_mfma_f32_16x16x32_bf16 v[118:121], v[166:169], v[202:205], v[118:121]
	v_mfma_f32_16x16x32_bf16 v[114:117], v[174:177], v[202:205], v[114:117]
	v_mfma_f32_16x16x32_bf16 v[102:105], v[166:169], v[212:215], v[102:105]
	v_mfma_f32_16x16x32_bf16 v[98:101], v[174:177], v[212:215], v[98:101]
	v_mfma_f32_16x16x32_bf16 v[86:89], v[166:169], v[220:223], v[86:89]
	v_mfma_f32_16x16x32_bf16 v[82:85], v[174:177], v[220:223], v[82:85]
	v_mfma_f32_16x16x32_bf16 v[70:73], v[166:169], v[228:231], v[70:73]
	v_mfma_f32_16x16x32_bf16 v[66:69], v[174:177], v[228:231], v[66:69]
	v_mfma_f32_16x16x32_bf16 v[118:121], v[170:173], v[208:211], v[118:121]
	v_mfma_f32_16x16x32_bf16 v[114:117], v[178:181], v[208:211], v[114:117]
	v_mfma_f32_16x16x32_bf16 v[102:105], v[170:173], v[216:219], v[102:105]
	v_mfma_f32_16x16x32_bf16 v[98:101], v[178:181], v[216:219], v[98:101]
	v_mfma_f32_16x16x32_bf16 v[86:89], v[170:173], v[224:227], v[86:89]
	v_mfma_f32_16x16x32_bf16 v[82:85], v[178:181], v[224:227], v[82:85]
	v_mfma_f32_16x16x32_bf16 v[70:73], v[170:173], v[232:235], v[70:73]
	v_mfma_f32_16x16x32_bf16 v[66:69], v[178:181], v[232:235], v[66:69]
	s_setprio 0
	s_barrier
	v_add_u32_e32 v136, 0x10000, v147
	ds_read_b128 v[166:169], v136
	ds_read_b128 v[170:173], v136 offset:1024
	ds_read_b128 v[174:177], v136 offset:2048
	ds_read_b128 v[178:181], v136 offset:3072
	ds_read_b128 v[202:205], v165 offset:16384
	ds_read_b128 v[208:211], v165 offset:17408
	ds_read_b128 v[212:215], v165 offset:18432
	ds_read_b128 v[216:219], v165 offset:19456
	ds_read_b128 v[220:223], v165 offset:20480
	ds_read_b128 v[224:227], v165 offset:21504
	ds_read_b128 v[228:231], v165 offset:22528
	ds_read_b128 v[232:235], v165 offset:23552
	v_lshl_add_u64 v[136:137], s[76:77], 0, v[0:1]
	s_add_i32 m0, s94, 0x8000
	v_lshl_add_u64 v[144:145], s[76:77], 0, v[130:131]
	global_load_lds_dwordx4 v[136:137], off
	s_add_i32 m0, s94, 0xa000
	s_nop 0
	global_load_lds_dwordx4 v[144:145], off
	v_lshl_add_u64 v[182:183], vcc, 0, v[0:1]
	s_add_i32 m0, s93, 0x1c000
	v_lshl_add_u64 v[236:237], vcc, 0, v[130:131]
	global_load_lds_dwordx4 v[182:183], off
	s_add_i32 m0, s93, 0x1e000
	s_nop 0
	global_load_lds_dwordx4 v[236:237], off
	s_cmp_lt_u32 s82, s59
	s_cselect_b32 s83, 0x80, 0
	s_add_u32 s76, s76, s83
	s_addc_u32 s77, s77, 0
	s_add_u32 vcc_lo, vcc_lo, s83
	s_addc_u32 vcc_hi, vcc_hi, 0
	s_add_i32 s82, s82, 1
	s_waitcnt vmcnt(8)
	s_waitcnt lgkmcnt(0)
	s_barrier
; #define PG8_STAGE(bufoff, gbase, voff) do { _Pragma("unroll") for (int _i = 0; _i < 2; ++_i) \
;         __builtin_amdgcn_global_load_lds((const unsigned*)((const char*)(gbase) + (voff)[_i]), (PG8_LAS unsigned*)(lds + (bufoff) + ldsw + _i * 8192), 16, 0, 0); } while (0)
; #define PG8_LDA(dst, b, h) do { _Pragma("unroll") for (int m = 0; m < 4; ++m) _Pragma("unroll") for (int k = 0; k < 2; ++k) dst[m][k] = *(const PG8_LAS bf16x8*)(lds + PG8_SA(b, h) + aoff + m * 2048 + k * 1024); } while (0)
; #define PG8_LDB(dst, b, h) do { _Pragma("unroll") for (int n = 0; n < 2; ++n) _Pragma("unroll") for (int k = 0; k < 2; ++k) dst[n][k] = *(const PG8_LAS bf16x8*)(lds + PG8_SB(b, h) + boff + n * 2048 + k * 1024); } while (0)
; template <class Epi, class Sched, bool ALIGN_EPI = false, bool SP2 = false>
; __device__ __forceinline__ void gemm_phase(PG8_LAS unsigned char* lds, const Gemm g, const Sched& S, const Epi& E) {
;     ...
;         PG8_STAGE(PG8_SB(0, 0), cB, voffB); PG8_STAGE(PG8_SB(0, 1), cB + hstep, voffB); PG8_STAGE(PG8_SA(0, 0), cA, voffA); PG8_STAGE(PG8_SA(0, 1), cA + hstep, voffA);
;         if (wr == 1) PG8_BAR;
;         PG8_WAIT_V(2); PG8_BAR;
;         PG8_STAGE(PG8_SB(1, 0), cB + kstep, voffB); PG8_STAGE(PG8_SA(1, 0), cA + kstep, voffA); PG8_STAGE(PG8_SB(1, 1), cB + hstep + kstep, voffB);
;         PG8_WAIT_V(6); PG8_BAR;
;     ...
;             PG8_LDB(B0, 0, 0); PG8_LDB(B1, 0, 1); PG8_SCHED; PG8_LDA(At, 0, 0); PG8_STAGE(PG8_SA(1, 1), a1 + hstep, voffA);
;             PG8_WAIT_V(8); PG8_WAIT_L(0); PG8_BAR; PG8_MMA(0, 0, At, B0); PG8_MMA(0, 1, At, B1); PG8_BAR; PG8_SCHED;
;             PG8_LDA(At, 0, 1); PG8_STAGE(PG8_SB(0, 0), b2, voffB); PG8_STAGE(PG8_SB(0, 1), b2 + hstep, voffB); PG8_STAGE(PG8_SA(0, 0), a2, voffA);
;             PG8_WAIT_V(8); PG8_WAIT_L(0); PG8_BAR; PG8_MMA(1, 0, At, B0); PG8_MMA(1, 1, At, B1); PG8_BAR; PG8_SCHED;
;             PG8_LDB(B0, 1, 0); PG8_LDB(B1, 1, 1); PG8_SCHED; PG8_LDA(At, 1, 0); PG8_STAGE(PG8_SA(0, 1), a2 + hstep, voffA);
;             PG8_WAIT_V(8); PG8_WAIT_L(0); PG8_BAR; PG8_MMA(0, 0, At, B0); PG8_MMA(0, 1, At, B1); PG8_BAR; PG8_SCHED;
;             PG8_LDA(At, 1, 1); PG8_STAGE(PG8_SB(1, 0), b3, voffB); PG8_STAGE(PG8_SB(1, 1), b3 + hstep, voffB); PG8_STAGE(PG8_SA(1, 0), a3, voffA);
;             PG8_WAIT_V(8); PG8_WAIT_L(0); PG8_BAR; PG8_MMA(1, 0, At, B0); PG8_MMA(1, 1, At, B1); PG8_BAR; PG8_SCHED;
	s_setprio 1
	v_mfma_f32_16x16x32_bf16 v[118:121], v[166:169], v[202:205], v[118:121]
	v_mfma_f32_16x16x32_bf16 v[114:117], v[174:177], v[202:205], v[114:117]
	v_mfma_f32_16x16x32_bf16 v[102:105], v[166:169], v[212:215], v[102:105]
	v_mfma_f32_16x16x32_bf16 v[98:101], v[174:177], v[212:215], v[98:101]
	v_mfma_f32_16x16x32_bf16 v[86:89], v[166:169], v[220:223], v[86:89]
	v_mfma_f32_16x16x32_bf16 v[82:85], v[174:177], v[220:223], v[82:85]
	v_mfma_f32_16x16x32_bf16 v[70:73], v[166:169], v[228:231], v[70:73]
	v_mfma_f32_16x16x32_bf16 v[66:69], v[174:177], v[228:231], v[66:69]
	v_mfma_f32_16x16x32_bf16 v[118:121], v[170:173], v[208:211], v[118:121]
	v_mfma_f32_16x16x32_bf16 v[114:117], v[178:181], v[208:211], v[114:117]
	v_mfma_f32_16x16x32_bf16 v[102:105], v[170:173], v[216:219], v[102:105]
	v_mfma_f32_16x16x32_bf16 v[98:101], v[178:181], v[216:219], v[98:101]
	v_mfma_f32_16x16x32_bf16 v[86:89], v[170:173], v[224:227], v[86:89]
	v_mfma_f32_16x16x32_bf16 v[82:85], v[178:181], v[224:227], v[82:85]
	v_mfma_f32_16x16x32_bf16 v[70:73], v[170:173], v[232:235], v[70:73]
	v_mfma_f32_16x16x32_bf16 v[66:69], v[178:181], v[232:235], v[66:69]
	s_setprio 0
	s_barrier
	v_add_u32_e32 v136, 0x18000, v147
	ds_read_b128 v[166:169], v136
	ds_read_b128 v[170:173], v136 offset:1024
	ds_read_b128 v[174:177], v136 offset:2048
	ds_read_b128 v[178:181], v136 offset:3072
	ds_read_b128 v[202:205], v165 offset:49152
	ds_read_b128 v[208:211], v165 offset:50176
	ds_read_b128 v[212:215], v165 offset:51200
	ds_read_b128 v[216:219], v165 offset:52224
	ds_read_b128 v[220:223], v165 offset:53248
	ds_read_b128 v[224:227], v165 offset:54272
	ds_read_b128 v[228:231], v165 offset:55296
	ds_read_b128 v[232:235], v165 offset:56320
	v_lshl_add_u64 v[136:137], s[76:77], 0, v[0:1]
	s_add_i32 m0, s94, 0x4000
	v_lshl_add_u64 v[144:145], s[76:77], 0, v[130:131]
	global_load_lds_dwordx4 v[136:137], off
	s_add_i32 m0, s94, 0x6000
	s_nop 0
	global_load_lds_dwordx4 v[144:145], off
	v_lshl_add_u64 v[182:183], vcc, 0, v[0:1]
	s_add_i32 m0, s93, 0x10000
	v_lshl_add_u64 v[236:237], vcc, 0, v[130:131]
	global_load_lds_dwordx4 v[182:183], off
	s_add_i32 m0, s93, 0x12000
	s_nop 0
	global_load_lds_dwordx4 v[236:237], off
	s_cmp_lt_u32 s82, s59
	s_cselect_b32 s83, 0x80, 0
	s_add_u32 s76, s76, s83
	s_addc_u32 s77, s77, 0
	s_add_u32 vcc_lo, vcc_lo, s83
	s_addc_u32 vcc_hi, vcc_hi, 0
	s_add_i32 s82, s82, 1
	s_waitcnt vmcnt(8)
	s_waitcnt lgkmcnt(0)
	s_barrier
	s_setprio 1
	v_mfma_f32_16x16x32_bf16 v[118:121], v[166:169], v[202:205], v[118:121]
	v_mfma_f32_16x16x32_bf16 v[114:117], v[174:177], v[202:205], v[114:117]
	v_mfma_f32_16x16x32_bf16 v[102:105], v[166:169], v[212:215], v[102:105]
	v_mfma_f32_16x16x32_bf16 v[98:101], v[174:177], v[212:215], v[98:101]
	v_mfma_f32_16x16x32_bf16 v[86:89], v[166:169], v[220:223], v[86:89]
	v_mfma_f32_16x16x32_bf16 v[82:85], v[174:177], v[220:223], v[82:85]
	v_mfma_f32_16x16x32_bf16 v[70:73], v[166:169], v[228:231], v[70:73]
	v_mfma_f32_16x16x32_bf16 v[66:69], v[174:177], v[228:231], v[66:69]
	v_mfma_f32_16x16x32_bf16 v[118:121], v[170:173], v[208:211], v[118:121]
	v_mfma_f32_16x16x32_bf16 v[114:117], v[178:181], v[208:211], v[114:117]
	v_mfma_f32_16x16x32_bf16 v[102:105], v[170:173], v[216:219], v[102:105]
	v_mfma_f32_16x16x32_bf16 v[98:101], v[178:181], v[216:219], v[98:101]
	v_mfma_f32_16x16x32_bf16 v[86:89], v[170:173], v[224:227], v[86:89]
	v_mfma_f32_16x16x32_bf16 v[82:85], v[178:181], v[224:227], v[82:85]
	v_mfma_f32_16x16x32_bf16 v[70:73], v[170:173], v[232:235], v[70:73]
	v_mfma_f32_16x16x32_bf16 v[66:69], v[178:181], v[232:235], v[66:69]
	s_setprio 0
	s_barrier
	s_add_i32 s83, s82, -3
	s_cmp_lt_u32 s83, s79
	s_cbranch_scc1 .Lkq_3_loop
	s_mov_b64 s[76:77], s[8:9]
	s_mov_b64 vcc, s[46:47]
	v_lshl_add_u64 v[136:137], vcc, 0, v[0:1]
	s_add_i32 m0, s93, 0x10000
	v_lshl_add_u64 v[144:145], vcc, 0, v[130:131]
	global_load_lds_dwordx4 v[136:137], off
	s_add_i32 m0, s93, 0x12000
	s_nop 0
	global_load_lds_dwordx4 v[144:145], off
	s_add_u32 vcc_lo, vcc_lo, s10
	s_addc_u32 vcc_hi, vcc_hi, 0
	v_lshl_add_u64 v[136:137], vcc, 0, v[0:1]
	s_add_i32 m0, s93, 0x14000
	v_lshl_add_u64 v[144:145], vcc, 0, v[130:131]
	global_load_lds_dwordx4 v[136:137], off
	s_add_i32 m0, s93, 0x16000
	s_nop 0
	global_load_lds_dwordx4 v[144:145], off
	v_lshl_add_u64 v[136:137], s[76:77], 0, v[0:1]
	s_add_i32 m0, s94, 0x0
	v_lshl_add_u64 v[144:145], s[76:77], 0, v[130:131]
	global_load_lds_dwordx4 v[136:137], off
	s_add_i32 m0, s94, 0x2000
	s_nop 0
	global_load_lds_dwordx4 v[144:145], off
	s_add_u32 s76, s76, s10
	s_addc_u32 s77, s77, 0
	v_lshl_add_u64 v[136:137], s[76:77], 0, v[0:1]
	s_add_i32 m0, s94, 0x4000
	v_lshl_add_u64 v[144:145], s[76:77], 0, v[130:131]
	global_load_lds_dwordx4 v[136:137], off
	s_add_i32 m0, s94, 0x6000
	s_nop 0
	global_load_lds_dwordx4 v[144:145], off
	s_add_u32 s76, s8, 0x80
	s_addc_u32 s77, s9, 0
	s_add_u32 vcc_lo, s46, 0x80
	s_addc_u32 vcc_hi, s47, 0
	v_lshl_add_u64 v[136:137], vcc, 0, v[0:1]
	s_add_i32 m0, s93, 0x18000
	v_lshl_add_u64 v[144:145], vcc, 0, v[130:131]
	global_load_lds_dwordx4 v[136:137], off
	s_add_i32 m0, s93, 0x1a000
	s_nop 0
	global_load_lds_dwordx4 v[144:145], off
	s_add_u32 vcc_lo, vcc_lo, s10
	s_addc_u32 vcc_hi, vcc_hi, 0
	v_lshl_add_u64 v[136:137], vcc, 0, v[0:1]
	s_add_i32 m0, s93, 0x1c000
	v_lshl_add_u64 v[144:145], vcc, 0, v[130:131]
	global_load_lds_dwordx4 v[136:137], off
	s_add_i32 m0, s93, 0x1e000
	s_nop 0
	global_load_lds_dwordx4 v[144:145], off
	v_lshl_add_u64 v[136:137], s[76:77], 0, v[0:1]
	s_add_i32 m0, s94, 0x8000
	v_lshl_add_u64 v[144:145], s[76:77], 0, v[130:131]
	global_load_lds_dwordx4 v[136:137], off
	s_add_i32 m0, s94, 0xa000
	s_nop 0
	global_load_lds_dwordx4 v[144:145], off
	s_branch .Lkq_exit
	s_nop 0

.LBB0_971:
	s_cmp_lt_u32 s20, 0x40001
	s_mov_b64 s[16:17], 0
	s_cselect_b64 s[18:19], -1, 0
	s_and_b64 vcc, exec, s[18:19]
	s_cbranch_vccnz .LBB0_968
	s_branch .LBB0_965
	s_nop 0
	s_nop 0
	s_nop 0
	s_nop 0
	s_nop 0
	s_nop 0
	s_nop 0
	s_nop 0
	s_nop 0
	s_nop 0
	s_nop 0
	s_nop 0
	s_nop 0
	s_nop 0
	s_nop 0
